# v6 + p2a: half of the workgroups run the pool mixer before their FFT units (others after) so streaming and LDS-bound work overlap across CUs
# speedup vs baseline: 1.0500x; 1.0033x over previous
.LBB0_532:
	s_or_b64 exec, exec, s[16:17]
	s_mov_b32 s101, 0
	s_bitcmp1_b32 s2, 3
	s_cbranch_scc0 .Lsw_fft
	s_mov_b32 s101, 1
	s_branch .LBB0_574
.Lsw_fft:
	s_add_u32 s42, s40, 0x16000000
	s_addc_u32 s43, s41, 0
	s_cmpk_lt_i32 s1, 0x300
	s_cselect_b64 s[16:17], -1, 0
	s_and_b64 vcc, exec, s[16:17]
	s_cbranch_vccz .LBB0_538
	s_cmpk_lt_i32 s1, 0x200
	s_cselect_b64 s[38:39], -1, 0
	s_lshl_b32 s19, s1, 6
	s_cmpk_gt_i32 s1, 0x1ff
	s_mov_b64 s[44:45], -1
	s_cbranch_scc0 .LBB0_535
	s_add_i32 s10, s19, 0x7fff8000
	s_and_b32 s22, s10, 0x7ffff800
	s_lshl_b32 s10, s1, 3
	s_and_b32 s10, s10, 0xf8
	s_mov_b64 s[44:45], 0

.LBB0_574:
	s_cmp_eq_u32 s101, 2
	s_cbranch_scc1 .LBB0_616
	v_cmp_gt_i32_e32 vcc, s82, v94
	s_and_saveexec_b64 s[16:17], vcc
	s_cbranch_execz .LBB0_615
	s_waitcnt vmcnt(0)
	v_and_b32_e32 v4, 31, v138
	v_lshlrev_b32_e32 v0, 4, v4
	v_lshl_add_u64 v[2:3], s[40:41], 0, v[0:1]
	s_mov_b64 s[0:1], 0x8800800
	v_bfe_u32 v5, v138, 3, 2
	v_lshl_add_u64 v[96:97], v[2:3], 0, s[0:1]
	s_mov_b64 s[0:1], 0x8800000
	v_lshlrev_b32_e64 v95, v5, 1
	v_cmp_eq_u32_e64 s[38:39], 3, v5
	v_cmp_lt_u32_e64 s[40:41], 15, v4
	v_cmp_lt_u32_e64 s[42:43], 7, v4
	v_lshl_add_u64 v[98:99], v[2:3], 0, s[0:1]
	v_cmp_gt_u32_e64 s[44:45], 8, v4
	s_mov_b64 s[22:23], 0
	s_branch .LBB0_577

.LBB0_615:
	s_or_b64 exec, exec, s[16:17]
	s_cmp_eq_u32 s101, 1
	s_cbranch_scc0 .Lsw_p2a_done
	s_mov_b32 s101, 2
	v_mov_b32_e32 v82, v233
	s_mov_b32 s1, s2
	v_mov_b32_e32 v138, v232
	s_mov_b32 s0, s71
	s_mov_b64 s[40:41], s[76:77]
	s_branch .Lsw_fft
.Lsw_p2a_done:
.LBB0_616:
	s_and_b64 s[0:1], s[66:67], s[14:15]
	s_and_b64 s[12:13], s[0:1], s[12:13]
	v_readlane_b32 s0, v255, 36
	s_add_i32 s0, s0, 4
	s_cmp_lt_i32 s0, s79
	s_cselect_b64 s[18:19], -1, 0
	s_and_b64 s[12:13], s[12:13], s[18:19]
	s_andn2_b64 vcc, exec, s[12:13]
	s_cbranch_vccnz .LBB0_666
	s_waitcnt vmcnt(0)
	s_waitcnt vmcnt(0)
	s_barrier
	s_mov_b64 s[12:13], exec
	v_readlane_b32 s14, v255, 22
	v_readlane_b32 s15, v255, 23
	s_and_b64 s[14:15], s[12:13], s[14:15]
	s_mov_b64 exec, s[14:15]
	s_cbranch_execz .LBB0_665
	v_mov_b32_e32 v0, s70
	s_waitcnt vmcnt(0) expcnt(0) lgkmcnt(0)
	ds_read_b32 v3, v0
	ds_read_b32 v2, v0 offset:4
	s_waitcnt lgkmcnt(1)
	v_cmp_ne_u32_e32 vcc, 0, v3
	s_cbranch_vccnz .LBB0_633
	v_readlane_b32 s16, v254, 0
	v_readlane_b32 s17, v254, 1
	s_load_dwordx2 s[14:15], s[16:17], 0x4
	s_mov_b32 s5, 1
	s_waitcnt lgkmcnt(0)
	s_mul_i32 s1, s14, s3
	s_mul_i32 s1, s1, s15
	s_branch .LBB0_621

	.amdhsa_kernel _Z8hpge_fwd6Params
		.amdhsa_group_segment_fixed_size 0
		.amdhsa_private_segment_fixed_size 0
		.amdhsa_kernarg_size 416
		.amdhsa_user_sgpr_count 2
		.amdhsa_user_sgpr_dispatch_ptr 0
		.amdhsa_user_sgpr_queue_ptr 0
		.amdhsa_user_sgpr_kernarg_segment_ptr 1
		.amdhsa_user_sgpr_dispatch_id 0
		.amdhsa_user_sgpr_kernarg_preload_length 0
		.amdhsa_user_sgpr_kernarg_preload_offset 0
		.amdhsa_user_sgpr_private_segment_size 0
		.amdhsa_uses_dynamic_stack 0
		.amdhsa_enable_private_segment 0
		.amdhsa_system_sgpr_workgroup_id_x 1
		.amdhsa_system_sgpr_workgroup_id_y 0
		.amdhsa_system_sgpr_workgroup_id_z 0
		.amdhsa_system_sgpr_workgroup_info 0
		.amdhsa_system_vgpr_workitem_id 2
		.amdhsa_next_free_vgpr 256
		.amdhsa_next_free_sgpr 102
		.amdhsa_accum_offset 256
		.amdhsa_reserve_vcc 1
		.amdhsa_float_round_mode_32 0
		.amdhsa_float_round_mode_16_64 0
		.amdhsa_float_denorm_mode_32 3
		.amdhsa_float_denorm_mode_16_64 3
		.amdhsa_dx10_clamp 1
		.amdhsa_ieee_mode 1
		.amdhsa_fp16_overflow 0
		.amdhsa_tg_split 0
		.amdhsa_exception_fp_ieee_invalid_op 0
		.amdhsa_exception_fp_denorm_src 0
		.amdhsa_exception_fp_ieee_div_zero 0
		.amdhsa_exception_fp_ieee_overflow 0
		.amdhsa_exception_fp_ieee_underflow 0
		.amdhsa_exception_fp_ieee_inexact 0
		.amdhsa_exception_int_div_zero 0
	.end_amdhsa_kernel

amdhsa.kernels:
  - .agpr_count:     0
    .args:
      - .offset:         0
        .size:           160
        .value_kind:     by_value
      - .offset:         160
        .size:           4
        .value_kind:     hidden_block_count_x
      - .offset:         164
        .size:           4
        .value_kind:     hidden_block_count_y
      - .offset:         168
        .size:           4
        .value_kind:     hidden_block_count_z
      - .offset:         172
        .size:           2
        .value_kind:     hidden_group_size_x
      - .offset:         174
        .size:           2
        .value_kind:     hidden_group_size_y
      - .offset:         176
        .size:           2
        .value_kind:     hidden_group_size_z
      - .offset:         178
        .size:           2
        .value_kind:     hidden_remainder_x
      - .offset:         180
        .size:           2
        .value_kind:     hidden_remainder_y
      - .offset:         182
        .size:           2
        .value_kind:     hidden_remainder_z
      - .offset:         200
        .size:           8
        .value_kind:     hidden_global_offset_x
      - .offset:         208
        .size:           8
        .value_kind:     hidden_global_offset_y
      - .offset:         216
        .size:           8
        .value_kind:     hidden_global_offset_z
      - .offset:         224
        .size:           2
        .value_kind:     hidden_grid_dims
      - .offset:         248
        .size:           8
        .value_kind:     hidden_multigrid_sync_arg
      - .offset:         280
        .size:           4
        .value_kind:     hidden_dynamic_lds_size
    .group_segment_fixed_size: 0
    .kernarg_segment_align: 8
    .kernarg_segment_size: 416
    .language:       OpenCL C
    .language_version:
      - 2
      - 0
    .max_flat_workgroup_size: 512
    .name:           _Z8hpge_fwd6Params
    .private_segment_fixed_size: 0
    .sgpr_count:     108
    .sgpr_spill_count: 103
    .symbol:         _Z8hpge_fwd6Params.kd
    .uniform_work_group_size: 1
    .uses_dynamic_stack: false
    .vgpr_count:     256
    .vgpr_spill_count: 0
    .wavefront_size: 64
